# v83 + nt on the attention Q-fragment loads and the final LayerNorm's first residual-row loads (both read once)
# baseline (speedup 1.0000x reference)
; __device__ __forceinline__ void attn_unit(const bf16* __restrict__ qkvb, int seq, int q0, int h, ldsp_t ldsb, float* wsc, const float* tab, float lam) {
;   int tid_ = threadIdx.x; asm volatile("" : "+v"(tid_));
;   const int tid = tid_, wid = __builtin_amdgcn_readfirstlane(tid >> 6), lane = tid & 63, r32 = lane & 31, hi = lane >> 5, mapw = wid >> 2, rg = wid & 3;
;   float* ws = wsc + wid * 64; float* li_l = ws; float* al_l = ws + 32;
;   float m_reg = -1e30f, l_reg = 0; bf16x8 qr[8]; f32x16 o[8];
; #pragma unroll
;   for (int d = 0; d < 8; ++d) o[d] = f32x16{};
;   const int q0w = q0 + rg * 32;
;   const bf16* Qw = qkvb + (long)(q0w + r32) * LD + h * 256 + mapw * 128 + hi * 8;
; #pragma unroll
;   for (int d0 = 0; d0 < 8; ++d0) qr[d0] = *reinterpret_cast<const bf16x8*>(Qw + d0 * 16);
;   unsigned koff0, voff0;
;   { const int row = 4 * wid + (lane >> 4), c = (lane & 15) ^ (row & 15); koff0 = (unsigned)(row * LD + 2048 + h * 256 + c * 8) * 2u; }
;   { const int subt = 2 * wid + (lane >> 5), kk = ((subt >> 3) << 3) | ((lane & 31) >> 2), key = (kk & ~0xC) | ((kk & 4) << 1) | ((kk & 8) >> 1), col = (subt & 7) * 32 + 8 * (lane & 3);
;     voff0 = (unsigned)(key * LD + 4096 + h * 256 + col) * 2u; }
;   const char* kvb = (const char*)qkvb;
;   const long tstep = 64L * LD * 2;
;     ...
;   const int NT = seq / 64;
;   const float cL = __int_as_float(__builtin_amdgcn_readfirstlane(__float_as_int(tab[0]))), cR = __int_as_float(__builtin_amdgcn_readfirstlane(__float_as_int(tab[256])));
;   ldsc_t kp[4];
; #pragma unroll
;   for (int d = 0; d < 4; ++d) kp[d] = (ldsc_t)ldsb + (mapw * 16384 + r32 * 256 + ((d * 32 + hi * 16) ^ ((r32 & 15) << 4)));
;   const int kd = (r32 & 8) ? -128 : 128;
;   const ldsc_t vp = (ldsc_t)ldsb + (V_OFF + v_rd_base(lane));
;   { _Pragma("unroll") for (int i = 0; i < 4; ++i) { DMA_K1(kvb, 0, i); DMA_V1(kvb, 0, i); } }
; __global__ void __launch_bounds__(NWAVES * 64, 2) fwd_kernel(Args args) {
;     ...
;             for (int ui = 0; ui < 4; ++ui) {
;                 const int uid = ui * F.G + F.vcu; if (uid >= Bc * 8 * nqb) break;
;                 const int bh = uid >> lgN2, qb = uid & (nqb - 1), b = bh >> 3, h = bh & 7;
;                 att3::attn_unit((const att3::bf16*)P_QKV + (size_t)b * S * QKVW, S, qb * 128, h, F.lds + RING_OFF, (float*)(lds + WSC_OFF), (const float*)(lds + TAB_OFF) + h * 260, lamfull);
.LBB0_546:
	s_mul_i32 s6, s13, s97
	s_add_i32 s6, s6, s33
	s_cmp_ge_i32 s6, s10
	s_mov_b64 s[4:5], -1
	s_cbranch_scc1 .LBB0_545
	s_ashr_i32 s5, s6, s42
	s_and_b32 s14, s6, s51
	s_mov_b32 s6, 22
	s_ashr_i32 s7, s6, 31
	s_ashr_i32 s4, s5, 3
	s_and_b32 s18, s5, 7
	s_lshl_b64 s[6:7], s[6:7], 3
	s_add_u32 s6, s0, s6
	s_addc_u32 s7, s1, s7
	s_load_dwordx2 s[8:9], s[6:7], 0x0
	s_ashr_i32 s5, s4, 31
	s_lshl_b64 s[6:7], s[4:5], s43
	s_mul_i32 s4, s7, 0x3000
	s_mul_hi_u32 s5, s6, 0x3000
	s_add_i32 s5, s5, s4
	s_mul_i32 s4, s6, 0x3000
	v_mov_b32_e32 v1, v245
	s_waitcnt lgkmcnt(0)
	s_add_u32 s8, s8, s4
	s_addc_u32 s9, s9, s5
	v_readfirstlane_b32 s16, v1
	s_mul_i32 s4, s18, 0x410
	s_ashr_i32 s24, s16, 6
	s_add_i32 s20, s4, 0
	s_lshl_b32 s4, s24, 5
	s_lshl_b32 s14, s14, 7
	s_and_b32 s17, s4, 0x60
	v_and_b32_e32 v247, 31, v1
	s_or_b32 s21, s17, s14
	v_or_b32_e32 v2, s21, v247
	v_mul_u32_u24_e32 v2, 0x1800, v2
	s_ashr_i32 s25, s16, 8
	v_lshlrev_b32_e32 v226, 1, v2
	v_lshl_add_u64 v[2:3], s[8:9], 0, v[226:227]
	s_lshl_b32 s84, s18, 9
	s_lshl_b32 s4, s25, 7
	v_lshl_add_u64 v[2:3], v[2:3], 0, s[84:85]
	s_ashr_i32 s5, s4, 31
	v_lshl_add_u64 v[2:3], s[4:5], 1, v[2:3]
	s_lshl_b32 s4, s24, 2
	v_bfe_u32 v10, v1, 4, 2
	v_bfe_u32 v248, v1, 5, 1
	v_bitop3_b32 v5, s4, v1, v10 bitop3:0x36
	v_lshlrev_b32_e32 v236, 4, v248
	v_mov_b32_e32 v237, v227
	v_or_b32_e32 v4, s4, v10
	v_lshlrev_b32_e32 v5, 3, v5
	s_lshl_b32 s4, s24, 1
	s_lshl_b32 s15, s18, 8
	v_lshl_add_u64 v[2:3], v[2:3], 0, v[236:237]
	v_mul_lo_u32 v4, v4, s67
	v_and_b32_e32 v11, 0x78, v5
	s_and_b32 s5, s4, 0x1ffff0
	v_lshrrev_b32_e32 v5, 1, v1
	v_or3_b32 v6, v4, v11, s15
	v_bfe_u32 v4, v1, 2, 2
	s_and_b32 s18, s24, 4
	global_load_dwordx4 v[162:165], v[2:3], off offset:224 nt
	global_load_dwordx4 v[166:169], v[2:3], off offset:192 nt
	global_load_dwordx4 v[170:173], v[2:3], off offset:160 nt
	global_load_dwordx4 v[174:177], v[2:3], off offset:128 nt
	global_load_dwordx4 v[178:181], v[2:3], off offset:96 nt
	global_load_dwordx4 v[182:185], v[2:3], off offset:64 nt
	global_load_dwordx4 v[186:189], v[2:3], off offset:32 nt
	global_load_dwordx4 v[190:193], v[2:3], off nt
	v_and_or_b32 v2, v5, 8, s5
	v_or3_b32 v2, s18, v4, v2
	v_and_or_b32 v7, s4, 6, v248
	v_lshlrev_b32_e32 v8, 3, v1
	v_mul_u32_u24_e32 v2, 0x1800, v2
	s_lshl_b32 s4, s24, 10
	s_add_i32 s20, s20, 0x20a00
	v_lshlrev_b32_e32 v7, 5, v7
	v_and_b32_e32 v12, 24, v8
	v_or_b32_e32 v13, s15, v2
	v_mov_b32_e32 v15, 0x1000
	s_add_i32 s23, s4, 0
	v_or3_b32 v2, v7, v12, v13
	v_mov_b32_e32 v14, 0x2000
	v_mov_b32_e32 v3, s20
	v_lshl_add_u32 v226, v6, 1, v15
	s_mov_b32 m0, s23
	v_lshl_add_u32 v2, v2, 1, v14
	ds_read2st64_b32 v[4:5], v3 offset1:4
	v_lshl_add_u64 v[6:7], s[8:9], 0, v[226:227]
	v_mov_b32_e32 v3, v227
	global_load_lds_dwordx4 v226, s[8:9]
	s_add_i32 m0, s23, 0x8000
	v_lshl_add_u64 v[8:9], s[8:9], 0, v[2:3]
	global_load_lds_dwordx4 v2, s[8:9]
	v_lshl_add_u64 v[2:3], v[6:7], 0, s[90:91]
	s_add_i32 m0, s23, 0x2000
	s_mov_b64 s[4:5], 0x30000
	global_load_lds_dwordx4 v[2:3], off
	v_lshl_add_u64 v[2:3], v[8:9], 0, s[4:5]
	s_add_i32 m0, s23, 0xa000
	s_mov_b64 s[4:5], 0x100
	global_load_lds_dwordx4 v[2:3], off
	v_lshl_add_u64 v[2:3], v[6:7], 0, s[4:5]
	s_add_i32 m0, s23, 0x4000
	s_mov_b64 s[4:5], 0x60100
	global_load_lds_dwordx4 v[2:3], off
	v_lshl_add_u64 v[2:3], v[8:9], 0, s[90:91]
	s_add_i32 m0, s23, 0xc000
	s_waitcnt lgkmcnt(0)
; __device__ __forceinline__ int v_rd_base(int lane) { return ((lane & 3) << 3) | (((lane >> 2) & 3) << 6) | (((lane >> 4) & 1) << 5) | (((lane >> 5) & 1) << 8); }
; #define DMA_K1(g_, b, i_) __builtin_amdgcn_global_load_lds((const unsigned*)((g_) + (((i_) & 1) * 32 * LD * 2 + ((i_) >> 1) * 256) + koff0), (__attribute__((address_space(3))) unsigned*)(ldsb + (b) * STAGE + (wid + 8 * (i_)) * 1024), 16, 0, 0)
; #define DMA_V1(g_, b, i_) __builtin_amdgcn_global_load_lds((const unsigned*)((g_) + ((i_) * 16 * LD * 2) + voff0), (__attribute__((address_space(3))) unsigned*)(ldsb + (b) * STAGE + V_OFF + (wid + 8 * (i_)) * 1024), 16, 0, 0)
; __device__ __forceinline__ void attn_unit(const bf16* __restrict__ qkvb, int seq, int q0, int h, ldsp_t ldsb, float* wsc, const float* tab, float lam) {
;     ...
;   float m_reg = -1e30f, l_reg = 0; bf16x8 qr[8]; f32x16 o[8];
; #pragma unroll
;   for (int d = 0; d < 8; ++d) o[d] = f32x16{};
;     ...
;   const int NT = seq / 64;
;   const float cL = __int_as_float(__builtin_amdgcn_readfirstlane(__float_as_int(tab[0]))), cR = __int_as_float(__builtin_amdgcn_readfirstlane(__float_as_int(tab[256])));
;   ldsc_t kp[4];
; #pragma unroll
;   for (int d = 0; d < 4; ++d) kp[d] = (ldsc_t)ldsb + (mapw * 16384 + r32 * 256 + ((d * 32 + hi * 16) ^ ((r32 & 15) << 4)));
;   const int kd = (r32 & 8) ? -128 : 128;
;   const ldsc_t vp = (ldsc_t)ldsb + (V_OFF + v_rd_base(lane));
;   { _Pragma("unroll") for (int i = 0; i < 4; ++i) { DMA_K1(kvb, 0, i); DMA_V1(kvb, 0, i); } }
;   asm volatile("s_waitcnt vmcnt(0)" : "+v"(qr[0]), "+v"(qr[1]), "+v"(qr[2]), "+v"(qr[3]), "+v"(qr[4]), "+v"(qr[5]), "+v"(qr[6]), "+v"(qr[7]) :: "memory");
	v_readfirstlane_b32 s19, v4
	global_load_lds_dwordx4 v[2:3], off
	v_lshl_add_u64 v[2:3], v[6:7], 0, s[4:5]
	s_add_i32 m0, s23, 0x6000
	s_mov_b64 s[4:5], 0x90000
	global_load_lds_dwordx4 v[2:3], off
	v_lshl_add_u64 v[2:3], v[8:9], 0, s[4:5]
	s_add_i32 m0, s23, 0xe000
	s_and_b32 s4, s16, 0x3fffffc0
	global_load_lds_dwordx4 v[2:3], off
	s_lshl_b32 s4, s4, 2
	s_add_i32 s18, s4, 0
	s_lshl_b32 s4, s25, 14
	v_lshlrev_b32_e32 v3, 4, v1
	s_add_i32 s4, s4, 0
	v_readfirstlane_b32 s22, v5
	v_and_b32_e32 v4, 0xf0, v3
	v_lshl_add_u32 v5, v247, 8, s4
	v_or_b32_e32 v6, 32, v236
	v_xad_u32 v253, v6, v4, v5
	v_or_b32_e32 v6, 64, v236
	v_and_b32_e32 v2, 63, v1
	v_xad_u32 v241, v6, v4, v5
	v_or_b32_e32 v6, 0x60, v236
	v_xad_u32 v252, v236, v4, v5
	v_xad_u32 v244, v6, v4, v5
	v_lshlrev_b32_e32 v5, 3, v2
	s_and_b32 s4, s24, 3
	v_and_b32_e32 v6, 24, v5
	v_and_b32_e32 v3, 0xc0, v3
	v_lshlrev_b32_e32 v7, 1, v1
	s_lshl_b32 s5, s4, 5
	v_and_b32_e32 v4, 8, v1
	v_and_b32_e32 v7, 32, v7
	v_and_b32_e32 v5, 0x100, v5
	v_add3_u32 v3, 0, v6, v3
	s_or_b32 s5, s5, s14
	v_add3_u32 v250, v3, v7, v5
	v_cmp_eq_u32_e32 vcc, 0, v4
	v_mov_b32_e32 v3, 0xffffff80
	v_mov_b32_e32 v4, 0x80
	s_sub_i32 s26, 0, s5
	s_mul_i32 s5, s24, 0x6000
	v_cndmask_b32_e32 v251, v3, v4, vcc
	v_cmp_gt_u32_e32 vcc, 32, v2
	v_mov_b32_e32 v2, s5
	v_mad_u32_u24 v2, v10, s67, v2
	v_or3_b32 v2, v2, s15, v11
	v_lshl_add_u32 v226, v2, 1, v15
	v_lshl_or_b32 v2, s4, 6, v13
	v_and_b32_e32 v1, 32, v1
	s_waitcnt vmcnt(0)
	s_waitcnt vmcnt(0)
	v_lshlrev_b32_e32 v3, 2, v248
	v_or3_b32 v1, v2, v1, v12
	v_mov_b32_e32 v98, v227
	v_mov_b32_e32 v99, v227
	v_mov_b32_e32 v112, v227
	v_mov_b32_e32 v113, v227
	v_mov_b32_e32 v0, v245
	s_add_i32 s18, s18, 0x20200
	v_sub_u32_e32 v245, v3, v247
	v_lshl_add_u32 v238, v1, 1, v14
	v_mov_b32_e32 v100, v227
	v_mov_b32_e32 v101, v227
	v_mov_b32_e32 v102, v227
	v_mov_b32_e32 v103, v227
	v_mov_b32_e32 v104, v227
	v_mov_b32_e32 v105, v227
	v_mov_b32_e32 v106, v227
	v_mov_b32_e32 v107, v227
	v_mov_b32_e32 v108, v227
	v_mov_b32_e32 v109, v227
	v_mov_b32_e32 v110, v227
	v_mov_b32_e32 v111, v227
	v_mov_b64_e32 v[128:129], v[112:113]
	v_mov_b64_e32 v[66:67], v[98:99]
	v_mov_b64_e32 v[82:83], v[98:99]
	v_mov_b64_e32 v[34:35], v[98:99]
	v_mov_b64_e32 v[50:51], v[98:99]
	v_mov_b64_e32 v[18:19], v[98:99]
	v_mov_b64_e32 v[2:3], v[98:99]
	v_mov_b32_e32 v242, 0x80008000
	v_mov_b32_e32 v246, 0x260
	v_mov_b32_e32 v240, 0x3727c5ac
	s_mov_b32 s25, 0
	v_lshl_add_u32 v237, v247, 2, s18
	v_mov_b32_e32 v239, v227
	v_mov_b32_e32 v249, 0
	v_mov_b32_e32 v211, 0xf149f2ca
	s_mov_b32 s27, 0x10000
	v_mov_b64_e32 v[126:127], v[110:111]
	v_mov_b64_e32 v[124:125], v[108:109]
	v_mov_b64_e32 v[122:123], v[106:107]
	v_mov_b64_e32 v[120:121], v[104:105]
	v_mov_b64_e32 v[118:119], v[102:103]
	v_mov_b64_e32 v[116:117], v[100:101]
	v_mov_b64_e32 v[114:115], v[98:99]
	v_mov_b64_e32 v[68:69], v[100:101]
	v_mov_b64_e32 v[70:71], v[102:103]
	v_mov_b64_e32 v[72:73], v[104:105]
	v_mov_b64_e32 v[74:75], v[106:107]
	v_mov_b64_e32 v[76:77], v[108:109]
	v_mov_b64_e32 v[78:79], v[110:111]
	v_mov_b64_e32 v[80:81], v[112:113]
	v_mov_b64_e32 v[84:85], v[100:101]
	v_mov_b64_e32 v[86:87], v[102:103]
	v_mov_b64_e32 v[88:89], v[104:105]
	v_mov_b64_e32 v[90:91], v[106:107]
	v_mov_b64_e32 v[92:93], v[108:109]
	v_mov_b64_e32 v[94:95], v[110:111]
	v_mov_b64_e32 v[96:97], v[112:113]
	v_mov_b64_e32 v[36:37], v[100:101]
	v_mov_b64_e32 v[38:39], v[102:103]
	v_mov_b64_e32 v[40:41], v[104:105]
	v_mov_b64_e32 v[42:43], v[106:107]
	v_mov_b64_e32 v[44:45], v[108:109]
	v_mov_b64_e32 v[46:47], v[110:111]
	v_mov_b64_e32 v[48:49], v[112:113]
	v_mov_b64_e32 v[52:53], v[100:101]
	v_mov_b64_e32 v[54:55], v[102:103]
	v_mov_b64_e32 v[56:57], v[104:105]
	v_mov_b64_e32 v[58:59], v[106:107]
	v_mov_b64_e32 v[60:61], v[108:109]
	v_mov_b64_e32 v[62:63], v[110:111]
	v_mov_b64_e32 v[64:65], v[112:113]
	v_mov_b64_e32 v[20:21], v[100:101]
	v_mov_b64_e32 v[22:23], v[102:103]
	v_mov_b64_e32 v[24:25], v[104:105]
	v_mov_b64_e32 v[26:27], v[106:107]
	v_mov_b64_e32 v[28:29], v[108:109]
	v_mov_b64_e32 v[30:31], v[110:111]
	v_mov_b64_e32 v[32:33], v[112:113]
	v_mov_b64_e32 v[4:5], v[100:101]
	v_mov_b64_e32 v[6:7], v[102:103]
	v_mov_b64_e32 v[8:9], v[104:105]
	v_mov_b64_e32 v[10:11], v[106:107]
	v_mov_b64_e32 v[12:13], v[108:109]
	v_mov_b64_e32 v[14:15], v[110:111]
	v_mov_b64_e32 v[16:17], v[112:113]
	v_add_u32_e32 v239, 0x30000, v238

; #define GAS __attribute__((address_space(1)))
; #define PHASE_TID() do { int t_ = threadIdx.x; asm volatile("" : "+v"(t_)); F.tid = t_; F.lane = t_ & 63; F.wave = __builtin_amdgcn_readfirstlane(t_ >> 6); asm volatile("" : "+s"(F.vcu), "+s"(F.G)); } while (0)
; #define KIN(i) ((const float*)karg(i))
; __device__ __forceinline__ void ln_rows_b(const Frame& F, const bf16* src, float* dstf, bf16* dstb, float* must, const float* gam, const float* bet, int nrows, bool poison) {
;     const int gw = F.vcu * NWAVES + F.wave, NGW = F.G * NWAVES;
;     v4u wn[4];
;     if (gw < nrows) { const GAS v4u* xr = (const GAS v4u*)(src + (size_t)gw * DM) + F.lane;
; #pragma unroll
;         for (int j = 0; j < 4; ++j) wn[j] = xr[64 * j]; }
; __global__ void __launch_bounds__(NWAVES * 64, 2) fwd_kernel(Args args) {
;     ...
;     if (IN(PH_TOTAL - 1)) {
;         PHASE_TID();
;         bool poison = false;
;         if (!MK_PER_PHASE) poison = __hip_atomic_load((gu32*)(ctl + CW_BAR + XB_TMO), RLX_AGENT) != 0u;
;         ln_rows_b(F, P_RB, KOUT + (size_t)(NCHUNK - 1) * TC * DM, nullptr, nullptr, KIN(16) + DM, KIN(17) + DM, TC, poison);
.LBB0_1071:
	s_load_dwordx2 s[2:3], s[0:1], 0x98
	v_mov_b32_e32 v1, 0x4000
	s_lshl_b32 s4, s33, 3
	s_waitcnt lgkmcnt(0)
	global_load_dword v1, v1, s[2:3] offset:512 sc1
	v_readfirstlane_b32 s2, v245
	s_ashr_i32 s3, s2, 6
	s_add_i32 s4, s4, s3
	s_mov_b32 s10, 33
	s_mov_b32 s8, 18
	s_mov_b32 s6, 16
	s_mov_b32 s2, 17
	s_cmpk_gt_i32 s4, 0x3fff
	s_cbranch_scc1 .LBB0_1076
	s_ashr_i32 s11, s10, 31
	s_lshl_b64 s[10:11], s[10:11], 3
	s_add_u32 s10, s0, s10
	s_addc_u32 s11, s1, s11
	s_ashr_i32 s9, s8, 31
	s_lshl_b64 s[8:9], s[8:9], 3
	s_add_u32 s8, s0, s8
	s_addc_u32 s9, s1, s9
	s_ashr_i32 s7, s6, 31
	s_lshl_b64 s[6:7], s[6:7], 3
	s_add_u32 s12, s0, s6
	s_addc_u32 s13, s1, s7
	s_ashr_i32 s3, s2, 31
	s_lshl_b32 s6, s97, 3
	s_lshl_b64 s[2:3], s[2:3], 3
	s_add_u32 s0, s0, s2
	s_addc_u32 s1, s1, s3
	s_load_dwordx2 s[2:3], s[0:1], 0x0
	s_load_dwordx2 s[14:15], s[12:13], 0x0
	s_load_dwordx2 s[16:17], s[10:11], 0x0
	s_load_dwordx2 s[18:19], s[8:9], 0x0
	v_and_b32_e32 v2, 63, v245
	s_waitcnt lgkmcnt(0)
	s_add_u32 s2, s2, 0x2000
	s_addc_u32 s3, s3, 0
	s_add_u32 s8, s14, 0x2000
	s_addc_u32 s9, s15, 0
	s_ashr_i32 s5, s4, 31
	s_lshl_b64 s[0:1], s[4:5], 12
	s_add_u32 s0, s16, s0
	s_addc_u32 s1, s17, s1
	v_lshlrev_b32_e32 v0, 4, v2
	global_load_dwordx4 v[28:31], v0, s[0:1] nt
	global_load_dwordx4 v[24:27], v0, s[0:1] offset:1024 nt
	global_load_dwordx4 v[20:23], v0, s[0:1] offset:2048 nt
	global_load_dwordx4 v[16:19], v0, s[0:1] offset:3072 nt
	s_waitcnt vmcnt(0)
	v_cmp_eq_u32_e64 s[0:1], 0, v1
	v_mov_b32_e32 v1, 0
	v_lshlrev_b32_e32 v3, 2, v2
	v_lshlrev_b32_e32 v2, 5, v2
	v_or_b32_e32 v4, 0x800, v2
	v_mov_b32_e32 v5, v1
	v_lshl_add_u64 v[36:37], s[8:9], 0, v[4:5]
	v_lshl_add_u64 v[38:39], s[2:3], 0, v[4:5]
	v_or_b32_e32 v4, 0x1000, v2
	v_xor_b32_e32 v60, 4, v3
	v_xor_b32_e32 v61, 8, v3
	v_xor_b32_e32 v62, 16, v3
	v_xor_b32_e32 v63, 32, v3
	v_xor_b32_e32 v64, 64, v3
	v_xor_b32_e32 v65, 0x80, v3
	v_mov_b32_e32 v3, v1
	v_lshl_add_u64 v[40:41], s[8:9], 0, v[4:5]
	v_lshl_add_u64 v[42:43], s[2:3], 0, v[4:5]
	v_or_b32_e32 v4, 0x1800, v2
	v_lshl_add_u64 v[34:35], s[2:3], 0, v[2:3]
	v_lshl_add_u64 v[46:47], s[2:3], 0, v[4:5]
	s_lshl_b64 s[2:3], s[4:5], 13
	s_add_u32 s2, s18, s2
	s_addc_u32 s3, s19, s3
	v_lshl_add_u64 v[32:33], s[8:9], 0, v[2:3]
	v_lshl_add_u64 v[2:3], s[2:3], 0, v[2:3]
	s_mov_b64 s[2:3], 0x18000000
	v_lshl_add_u64 v[48:49], v[2:3], 0, s[2:3]
	s_add_i32 s2, s4, s6
	s_ashr_i32 s7, s6, 31
	s_ashr_i32 s3, s2, 31
	v_lshl_add_u64 v[44:45], s[8:9], 0, v[4:5]
	s_lshl_b64 s[8:9], s[6:7], 13
	s_lshl_b64 s[2:3], s[2:3], 12
	s_add_u32 s2, s16, s2
	s_addc_u32 s3, s17, s3
	s_movk_i32 s14, 0x1000
	v_lshl_add_u64 v[50:51], s[2:3], 0, v[0:1]
	s_lshl_b64 s[10:11], s[6:7], 12
	v_mov_b32_e32 v66, 0x3727c5ac
	s_mov_b32 s5, 0xf800000
	v_mov_b32_e32 v67, 0x260
	v_mov_b32_e32 v68, 0x7fc00000
	s_branch .LBB0_1074
